# same as previous version plus one wait state after each 128-bit store of the weight-transpose loop (ISA store-data WAR rule); no functional change
# baseline (speedup 1.0000x reference)
.Ltr_win_d:
	v_add_u32_e32 v11, s25, v10
	v_cmp_gt_u32_e32 vcc, 0xa60, v10
	s_mov_b64 s[44:45], vcc
	v_min_u32_e32 v11, 0xa5f, v11
	v_lshlrev_b32_e32 v11, 2, v11
	s_mul_i32 s0, s28, 0xa60000
	s_mul_i32 s1, s23, 0xa6000
	s_add_u32 s8, s52, s0
	s_addc_u32 s9, s53, 0
	s_add_u32 s8, s8, s1
	s_addc_u32 s9, s9, 0
	v_mul_u32_u24_e32 v12, 0x880, v10
	s_lshl_b32 s0, s23, 7
	v_add_u32_e32 v12, s0, v12
	v_readlane_b32 s78, v253, 7
	v_readlane_b32 s79, v253, 8
	s_mul_i32 s0, s28, 0x5d8000
	s_add_u32 s78, s78, s0
	s_addc_u32 s79, s79, 0
	s_mul_i32 s0, s28, 0x1000
	s_lshl_b32 s1, s23, 8
	s_add_u32 s20, s50, s0
	s_addc_u32 s21, s51, 0
	s_add_u32 s20, s20, s1
	s_addc_u32 s21, s21, 0
	global_load_dword v26, v11, s[8:9]
	s_add_u32 s8, s8, 0x2980
	s_addc_u32 s9, s9, 0
	global_load_dword v27, v11, s[8:9]
	s_add_u32 s8, s8, 0x2980
	s_addc_u32 s9, s9, 0
	global_load_dword v28, v11, s[8:9]
	s_add_u32 s8, s8, 0x2980
	s_addc_u32 s9, s9, 0
	global_load_dword v29, v11, s[8:9]
	s_add_u32 s8, s8, 0x2980
	s_addc_u32 s9, s9, 0
	global_load_dword v30, v11, s[8:9]
	s_add_u32 s8, s8, 0x2980
	s_addc_u32 s9, s9, 0
	global_load_dword v31, v11, s[8:9]
	s_add_u32 s8, s8, 0x2980
	s_addc_u32 s9, s9, 0
	global_load_dword v32, v11, s[8:9]
	s_add_u32 s8, s8, 0x2980
	s_addc_u32 s9, s9, 0
	global_load_dword v33, v11, s[8:9]
	s_add_u32 s8, s8, 0x2980
	s_addc_u32 s9, s9, 0
	global_load_dword v34, v11, s[8:9]
	s_add_u32 s8, s8, 0x2980
	s_addc_u32 s9, s9, 0
	global_load_dword v35, v11, s[8:9]
	s_add_u32 s8, s8, 0x2980
	s_addc_u32 s9, s9, 0
	global_load_dword v36, v11, s[8:9]
	s_add_u32 s8, s8, 0x2980
	s_addc_u32 s9, s9, 0
	global_load_dword v37, v11, s[8:9]
	s_add_u32 s8, s8, 0x2980
	s_addc_u32 s9, s9, 0
	global_load_dword v38, v11, s[8:9]
	s_add_u32 s8, s8, 0x2980
	s_addc_u32 s9, s9, 0
	global_load_dword v39, v11, s[8:9]
	s_add_u32 s8, s8, 0x2980
	s_addc_u32 s9, s9, 0
	global_load_dword v40, v11, s[8:9]
	s_add_u32 s8, s8, 0x2980
	s_addc_u32 s9, s9, 0
	global_load_dword v41, v11, s[8:9]
	s_add_u32 s8, s8, 0x2980
	s_addc_u32 s9, s9, 0
	global_load_dword v42, v11, s[8:9]
	s_add_u32 s8, s8, 0x2980
	s_addc_u32 s9, s9, 0
	global_load_dword v43, v11, s[8:9]
	s_add_u32 s8, s8, 0x2980
	s_addc_u32 s9, s9, 0
	global_load_dword v44, v11, s[8:9]
	s_add_u32 s8, s8, 0x2980
	s_addc_u32 s9, s9, 0
	global_load_dword v45, v11, s[8:9]
	s_add_u32 s8, s8, 0x2980
	s_addc_u32 s9, s9, 0
	global_load_dword v46, v11, s[8:9]
	s_add_u32 s8, s8, 0x2980
	s_addc_u32 s9, s9, 0
	global_load_dword v47, v11, s[8:9]
	s_add_u32 s8, s8, 0x2980
	s_addc_u32 s9, s9, 0
	global_load_dword v48, v11, s[8:9]
	s_add_u32 s8, s8, 0x2980
	s_addc_u32 s9, s9, 0
	global_load_dword v49, v11, s[8:9]
	s_add_u32 s8, s8, 0x2980
	s_addc_u32 s9, s9, 0
	global_load_dword v50, v11, s[8:9]
	s_add_u32 s8, s8, 0x2980
	s_addc_u32 s9, s9, 0
	global_load_dword v51, v11, s[8:9]
	s_add_u32 s8, s8, 0x2980
	s_addc_u32 s9, s9, 0
	global_load_dword v52, v11, s[8:9]
	s_add_u32 s8, s8, 0x2980
	s_addc_u32 s9, s9, 0
	global_load_dword v53, v11, s[8:9]
	s_add_u32 s8, s8, 0x2980
	s_addc_u32 s9, s9, 0
	global_load_dword v54, v11, s[8:9]
	s_add_u32 s8, s8, 0x2980
	s_addc_u32 s9, s9, 0
	global_load_dword v55, v11, s[8:9]
	s_add_u32 s8, s8, 0x2980
	s_addc_u32 s9, s9, 0
	global_load_dword v56, v11, s[8:9]
	s_add_u32 s8, s8, 0x2980
	s_addc_u32 s9, s9, 0
	global_load_dword v57, v11, s[8:9]
	s_add_u32 s8, s8, 0x2980
	s_addc_u32 s9, s9, 0
	s_load_dwordx8 s[88:95], s[20:21], 0x0
	s_waitcnt vmcnt(24)
	s_waitcnt lgkmcnt(0)
	v_mul_f32_e32 v26, s88, v26
	v_mul_f32_e32 v27, s89, v27
	v_mul_f32_e32 v28, s90, v28
	v_mul_f32_e32 v29, s91, v29
	v_mul_f32_e32 v30, s92, v30
	v_mul_f32_e32 v31, s93, v31
	v_mul_f32_e32 v32, s94, v32
	v_mul_f32_e32 v33, s95, v33
	v_cvt_pk_bf16_f32 v2, v26, v27
	v_cvt_pk_bf16_f32 v3, v28, v29
	v_cvt_pk_bf16_f32 v4, v30, v31
	v_cvt_pk_bf16_f32 v5, v32, v33
	v_cndmask_b32_e64 v2, 0, v2, s[44:45]
	v_cndmask_b32_e64 v3, 0, v3, s[44:45]
	v_cndmask_b32_e64 v4, 0, v4, s[44:45]
	v_cndmask_b32_e64 v5, 0, v5, s[44:45]
	global_store_dwordx4 v12, v[2:5], s[78:79] offset:0
	s_nop 0
	global_load_dword v58, v11, s[8:9]
	s_add_u32 s8, s8, 0x2980
	s_addc_u32 s9, s9, 0
	global_load_dword v59, v11, s[8:9]
	s_add_u32 s8, s8, 0x2980
	s_addc_u32 s9, s9, 0
	global_load_dword v60, v11, s[8:9]
	s_add_u32 s8, s8, 0x2980
	s_addc_u32 s9, s9, 0
	global_load_dword v61, v11, s[8:9]
	s_add_u32 s8, s8, 0x2980
	s_addc_u32 s9, s9, 0
	global_load_dword v62, v11, s[8:9]
	s_add_u32 s8, s8, 0x2980
	s_addc_u32 s9, s9, 0
	global_load_dword v63, v11, s[8:9]
	s_add_u32 s8, s8, 0x2980
	s_addc_u32 s9, s9, 0
	global_load_dword v64, v11, s[8:9]
	s_add_u32 s8, s8, 0x2980
	s_addc_u32 s9, s9, 0
	global_load_dword v65, v11, s[8:9]
	s_add_u32 s8, s8, 0x2980
	s_addc_u32 s9, s9, 0
	s_load_dwordx8 s[88:95], s[20:21], 0x20
	s_waitcnt vmcnt(25)
	s_waitcnt lgkmcnt(0)
	v_mul_f32_e32 v34, s88, v34
	v_mul_f32_e32 v35, s89, v35
	v_mul_f32_e32 v36, s90, v36
	v_mul_f32_e32 v37, s91, v37
	v_mul_f32_e32 v38, s92, v38
	v_mul_f32_e32 v39, s93, v39
	v_mul_f32_e32 v40, s94, v40
	v_mul_f32_e32 v41, s95, v41
	v_cvt_pk_bf16_f32 v2, v34, v35
	v_cvt_pk_bf16_f32 v3, v36, v37
	v_cvt_pk_bf16_f32 v4, v38, v39
	v_cvt_pk_bf16_f32 v5, v40, v41
	v_cndmask_b32_e64 v2, 0, v2, s[44:45]
	v_cndmask_b32_e64 v3, 0, v3, s[44:45]
	v_cndmask_b32_e64 v4, 0, v4, s[44:45]
	v_cndmask_b32_e64 v5, 0, v5, s[44:45]
	global_store_dwordx4 v12, v[2:5], s[78:79] offset:16
	s_nop 0
	global_load_dword v66, v11, s[8:9]
	s_add_u32 s8, s8, 0x2980
	s_addc_u32 s9, s9, 0
	global_load_dword v67, v11, s[8:9]
	s_add_u32 s8, s8, 0x2980
	s_addc_u32 s9, s9, 0
	global_load_dword v68, v11, s[8:9]
	s_add_u32 s8, s8, 0x2980
	s_addc_u32 s9, s9, 0
	global_load_dword v69, v11, s[8:9]
	s_add_u32 s8, s8, 0x2980
	s_addc_u32 s9, s9, 0
	global_load_dword v70, v11, s[8:9]
	s_add_u32 s8, s8, 0x2980
	s_addc_u32 s9, s9, 0
	global_load_dword v71, v11, s[8:9]
	s_add_u32 s8, s8, 0x2980
	s_addc_u32 s9, s9, 0
	global_load_dword v72, v11, s[8:9]
	s_add_u32 s8, s8, 0x2980
	s_addc_u32 s9, s9, 0
	global_load_dword v73, v11, s[8:9]
	s_add_u32 s8, s8, 0x2980
	s_addc_u32 s9, s9, 0
	s_load_dwordx8 s[88:95], s[20:21], 0x40
	s_waitcnt vmcnt(26)
	s_waitcnt lgkmcnt(0)
	v_mul_f32_e32 v42, s88, v42
	v_mul_f32_e32 v43, s89, v43
	v_mul_f32_e32 v44, s90, v44
	v_mul_f32_e32 v45, s91, v45
	v_mul_f32_e32 v46, s92, v46
	v_mul_f32_e32 v47, s93, v47
	v_mul_f32_e32 v48, s94, v48
	v_mul_f32_e32 v49, s95, v49
	v_cvt_pk_bf16_f32 v2, v42, v43
	v_cvt_pk_bf16_f32 v3, v44, v45
	v_cvt_pk_bf16_f32 v4, v46, v47
	v_cvt_pk_bf16_f32 v5, v48, v49
	v_cndmask_b32_e64 v2, 0, v2, s[44:45]
	v_cndmask_b32_e64 v3, 0, v3, s[44:45]
	v_cndmask_b32_e64 v4, 0, v4, s[44:45]
	v_cndmask_b32_e64 v5, 0, v5, s[44:45]
	global_store_dwordx4 v12, v[2:5], s[78:79] offset:32
	s_nop 0
	global_load_dword v74, v11, s[8:9]
	s_add_u32 s8, s8, 0x2980
	s_addc_u32 s9, s9, 0
	global_load_dword v75, v11, s[8:9]
	s_add_u32 s8, s8, 0x2980
	s_addc_u32 s9, s9, 0
	global_load_dword v76, v11, s[8:9]
	s_add_u32 s8, s8, 0x2980
	s_addc_u32 s9, s9, 0
	global_load_dword v77, v11, s[8:9]
	s_add_u32 s8, s8, 0x2980
	s_addc_u32 s9, s9, 0
	global_load_dword v78, v11, s[8:9]
	s_add_u32 s8, s8, 0x2980
	s_addc_u32 s9, s9, 0
	global_load_dword v79, v11, s[8:9]
	s_add_u32 s8, s8, 0x2980
	s_addc_u32 s9, s9, 0
	global_load_dword v80, v11, s[8:9]
	s_add_u32 s8, s8, 0x2980
	s_addc_u32 s9, s9, 0
	global_load_dword v81, v11, s[8:9]
	s_add_u32 s8, s8, 0x2980
	s_addc_u32 s9, s9, 0
	s_load_dwordx8 s[88:95], s[20:21], 0x60
	s_waitcnt vmcnt(27)
	s_waitcnt lgkmcnt(0)
	v_mul_f32_e32 v50, s88, v50
	v_mul_f32_e32 v51, s89, v51
	v_mul_f32_e32 v52, s90, v52
	v_mul_f32_e32 v53, s91, v53
	v_mul_f32_e32 v54, s92, v54
	v_mul_f32_e32 v55, s93, v55
	v_mul_f32_e32 v56, s94, v56
	v_mul_f32_e32 v57, s95, v57
	v_cvt_pk_bf16_f32 v2, v50, v51
	v_cvt_pk_bf16_f32 v3, v52, v53
	v_cvt_pk_bf16_f32 v4, v54, v55
	v_cvt_pk_bf16_f32 v5, v56, v57
	v_cndmask_b32_e64 v2, 0, v2, s[44:45]
	v_cndmask_b32_e64 v3, 0, v3, s[44:45]
	v_cndmask_b32_e64 v4, 0, v4, s[44:45]
	v_cndmask_b32_e64 v5, 0, v5, s[44:45]
	global_store_dwordx4 v12, v[2:5], s[78:79] offset:48
	s_nop 0
	global_load_dword v82, v11, s[8:9]
	s_add_u32 s8, s8, 0x2980
	s_addc_u32 s9, s9, 0
	global_load_dword v83, v11, s[8:9]
	s_add_u32 s8, s8, 0x2980
	s_addc_u32 s9, s9, 0
	global_load_dword v84, v11, s[8:9]
	s_add_u32 s8, s8, 0x2980
	s_addc_u32 s9, s9, 0
	global_load_dword v85, v11, s[8:9]
	s_add_u32 s8, s8, 0x2980
	s_addc_u32 s9, s9, 0
	global_load_dword v86, v11, s[8:9]
	s_add_u32 s8, s8, 0x2980
	s_addc_u32 s9, s9, 0
	global_load_dword v87, v11, s[8:9]
	s_add_u32 s8, s8, 0x2980
	s_addc_u32 s9, s9, 0
	global_load_dword v88, v11, s[8:9]
	s_add_u32 s8, s8, 0x2980
	s_addc_u32 s9, s9, 0
	global_load_dword v89, v11, s[8:9]
	s_add_u32 s8, s8, 0x2980
	s_addc_u32 s9, s9, 0
	s_load_dwordx8 s[88:95], s[20:21], 0x80
	s_waitcnt vmcnt(27)
	s_waitcnt lgkmcnt(0)
	v_mul_f32_e32 v58, s88, v58
	v_mul_f32_e32 v59, s89, v59
	v_mul_f32_e32 v60, s90, v60
	v_mul_f32_e32 v61, s91, v61
	v_mul_f32_e32 v62, s92, v62
	v_mul_f32_e32 v63, s93, v63
	v_mul_f32_e32 v64, s94, v64
	v_mul_f32_e32 v65, s95, v65
	v_cvt_pk_bf16_f32 v2, v58, v59
	v_cvt_pk_bf16_f32 v3, v60, v61
	v_cvt_pk_bf16_f32 v4, v62, v63
	v_cvt_pk_bf16_f32 v5, v64, v65
	v_cndmask_b32_e64 v2, 0, v2, s[44:45]
	v_cndmask_b32_e64 v3, 0, v3, s[44:45]
	v_cndmask_b32_e64 v4, 0, v4, s[44:45]
	v_cndmask_b32_e64 v5, 0, v5, s[44:45]
	global_store_dwordx4 v12, v[2:5], s[78:79] offset:64
	s_nop 0
	s_load_dwordx8 s[88:95], s[20:21], 0xa0
	s_waitcnt vmcnt(19)
	s_waitcnt lgkmcnt(0)
	v_mul_f32_e32 v66, s88, v66
	v_mul_f32_e32 v67, s89, v67
	v_mul_f32_e32 v68, s90, v68
	v_mul_f32_e32 v69, s91, v69
	v_mul_f32_e32 v70, s92, v70
	v_mul_f32_e32 v71, s93, v71
	v_mul_f32_e32 v72, s94, v72
	v_mul_f32_e32 v73, s95, v73
	v_cvt_pk_bf16_f32 v2, v66, v67
	v_cvt_pk_bf16_f32 v3, v68, v69
	v_cvt_pk_bf16_f32 v4, v70, v71
	v_cvt_pk_bf16_f32 v5, v72, v73
	v_cndmask_b32_e64 v2, 0, v2, s[44:45]
	v_cndmask_b32_e64 v3, 0, v3, s[44:45]
	v_cndmask_b32_e64 v4, 0, v4, s[44:45]
	v_cndmask_b32_e64 v5, 0, v5, s[44:45]
	global_store_dwordx4 v12, v[2:5], s[78:79] offset:80
	s_nop 0
	s_load_dwordx8 s[88:95], s[20:21], 0xc0
	s_waitcnt vmcnt(11)
	s_waitcnt lgkmcnt(0)
	v_mul_f32_e32 v74, s88, v74
	v_mul_f32_e32 v75, s89, v75
	v_mul_f32_e32 v76, s90, v76
	v_mul_f32_e32 v77, s91, v77
	v_mul_f32_e32 v78, s92, v78
	v_mul_f32_e32 v79, s93, v79
	v_mul_f32_e32 v80, s94, v80
	v_mul_f32_e32 v81, s95, v81
	v_cvt_pk_bf16_f32 v2, v74, v75
	v_cvt_pk_bf16_f32 v3, v76, v77
	v_cvt_pk_bf16_f32 v4, v78, v79
	v_cvt_pk_bf16_f32 v5, v80, v81
	v_cndmask_b32_e64 v2, 0, v2, s[44:45]
	v_cndmask_b32_e64 v3, 0, v3, s[44:45]
	v_cndmask_b32_e64 v4, 0, v4, s[44:45]
	v_cndmask_b32_e64 v5, 0, v5, s[44:45]
	global_store_dwordx4 v12, v[2:5], s[78:79] offset:96
	s_nop 0
	s_load_dwordx8 s[88:95], s[20:21], 0xe0
	s_waitcnt vmcnt(3)
	s_waitcnt lgkmcnt(0)
	v_mul_f32_e32 v82, s88, v82
	v_mul_f32_e32 v83, s89, v83
	v_mul_f32_e32 v84, s90, v84
	v_mul_f32_e32 v85, s91, v85
	v_mul_f32_e32 v86, s92, v86
	v_mul_f32_e32 v87, s93, v87
	v_mul_f32_e32 v88, s94, v88
	v_mul_f32_e32 v89, s95, v89
	v_cvt_pk_bf16_f32 v2, v82, v83
	v_cvt_pk_bf16_f32 v3, v84, v85
	v_cvt_pk_bf16_f32 v4, v86, v87
	v_cvt_pk_bf16_f32 v5, v88, v89
	v_cndmask_b32_e64 v2, 0, v2, s[44:45]
	v_cndmask_b32_e64 v3, 0, v3, s[44:45]
	v_cndmask_b32_e64 v4, 0, v4, s[44:45]
	v_cndmask_b32_e64 v5, 0, v5, s[44:45]
	global_store_dwordx4 v12, v[2:5], s[78:79] offset:112
	s_nop 0
	s_branch .Ltr_done
.Ltr_wout:
	s_lshl_b32 s24, s22, 6
	v_add_u32_e32 v10, s24, v221
	v_mov_b32_e32 v11, v10
	v_cmp_gt_u32_e32 vcc, 0x400, v10
	s_mov_b64 s[44:45], vcc
	v_min_u32_e32 v11, 0x3ff, v11
	v_lshlrev_b32_e32 v11, 2, v11
	s_mul_i32 s0, s28, 0x400000
	s_mul_i32 s1, s23, 0x40000
	s_add_u32 s8, s68, s0
	s_addc_u32 s9, s69, 0
	s_add_u32 s8, s8, s1
	s_addc_u32 s9, s9, 0
	v_mul_u32_u24_e32 v12, 0x880, v10
	s_lshl_b32 s0, s23, 7
	v_add_u32_e32 v12, s0, v12
	v_readlane_b32 s78, v253, 9
	v_readlane_b32 s79, v253, 10
	s_mul_i32 s0, s28, 0x220000
	s_add_u32 s78, s78, s0
	s_addc_u32 s79, s79, 0
	global_load_dword v26, v11, s[8:9]
	s_add_u32 s8, s8, 0x1000
	s_addc_u32 s9, s9, 0
	global_load_dword v27, v11, s[8:9]
	s_add_u32 s8, s8, 0x1000
	s_addc_u32 s9, s9, 0
	global_load_dword v28, v11, s[8:9]
	s_add_u32 s8, s8, 0x1000
	s_addc_u32 s9, s9, 0
	global_load_dword v29, v11, s[8:9]
	s_add_u32 s8, s8, 0x1000
	s_addc_u32 s9, s9, 0
	global_load_dword v30, v11, s[8:9]
	s_add_u32 s8, s8, 0x1000
	s_addc_u32 s9, s9, 0
	global_load_dword v31, v11, s[8:9]
	s_add_u32 s8, s8, 0x1000
	s_addc_u32 s9, s9, 0
	global_load_dword v32, v11, s[8:9]
	s_add_u32 s8, s8, 0x1000
	s_addc_u32 s9, s9, 0
	global_load_dword v33, v11, s[8:9]
	s_add_u32 s8, s8, 0x1000
	s_addc_u32 s9, s9, 0
	global_load_dword v34, v11, s[8:9]
	s_add_u32 s8, s8, 0x1000
	s_addc_u32 s9, s9, 0
	global_load_dword v35, v11, s[8:9]
	s_add_u32 s8, s8, 0x1000
	s_addc_u32 s9, s9, 0
	global_load_dword v36, v11, s[8:9]
	s_add_u32 s8, s8, 0x1000
	s_addc_u32 s9, s9, 0
	global_load_dword v37, v11, s[8:9]
	s_add_u32 s8, s8, 0x1000
	s_addc_u32 s9, s9, 0
	global_load_dword v38, v11, s[8:9]
	s_add_u32 s8, s8, 0x1000
	s_addc_u32 s9, s9, 0
	global_load_dword v39, v11, s[8:9]
	s_add_u32 s8, s8, 0x1000
	s_addc_u32 s9, s9, 0
	global_load_dword v40, v11, s[8:9]
	s_add_u32 s8, s8, 0x1000
	s_addc_u32 s9, s9, 0
	global_load_dword v41, v11, s[8:9]
	s_add_u32 s8, s8, 0x1000
	s_addc_u32 s9, s9, 0
	global_load_dword v42, v11, s[8:9]
	s_add_u32 s8, s8, 0x1000
	s_addc_u32 s9, s9, 0
	global_load_dword v43, v11, s[8:9]
	s_add_u32 s8, s8, 0x1000
	s_addc_u32 s9, s9, 0
	global_load_dword v44, v11, s[8:9]
	s_add_u32 s8, s8, 0x1000
	s_addc_u32 s9, s9, 0
	global_load_dword v45, v11, s[8:9]
	s_add_u32 s8, s8, 0x1000
	s_addc_u32 s9, s9, 0
	global_load_dword v46, v11, s[8:9]
	s_add_u32 s8, s8, 0x1000
	s_addc_u32 s9, s9, 0
	global_load_dword v47, v11, s[8:9]
	s_add_u32 s8, s8, 0x1000
	s_addc_u32 s9, s9, 0
	global_load_dword v48, v11, s[8:9]
	s_add_u32 s8, s8, 0x1000
	s_addc_u32 s9, s9, 0
	global_load_dword v49, v11, s[8:9]
	s_add_u32 s8, s8, 0x1000
	s_addc_u32 s9, s9, 0
	global_load_dword v50, v11, s[8:9]
	s_add_u32 s8, s8, 0x1000
	s_addc_u32 s9, s9, 0
	global_load_dword v51, v11, s[8:9]
	s_add_u32 s8, s8, 0x1000
	s_addc_u32 s9, s9, 0
	global_load_dword v52, v11, s[8:9]
	s_add_u32 s8, s8, 0x1000
	s_addc_u32 s9, s9, 0
	global_load_dword v53, v11, s[8:9]
	s_add_u32 s8, s8, 0x1000
	s_addc_u32 s9, s9, 0
	global_load_dword v54, v11, s[8:9]
	s_add_u32 s8, s8, 0x1000
	s_addc_u32 s9, s9, 0
	global_load_dword v55, v11, s[8:9]
	s_add_u32 s8, s8, 0x1000
	s_addc_u32 s9, s9, 0
	global_load_dword v56, v11, s[8:9]
	s_add_u32 s8, s8, 0x1000
	s_addc_u32 s9, s9, 0
	global_load_dword v57, v11, s[8:9]
	s_add_u32 s8, s8, 0x1000
	s_addc_u32 s9, s9, 0
	s_waitcnt vmcnt(24)
	v_cvt_pk_bf16_f32 v2, v26, v27
	v_cvt_pk_bf16_f32 v3, v28, v29
	v_cvt_pk_bf16_f32 v4, v30, v31
	v_cvt_pk_bf16_f32 v5, v32, v33
	v_cndmask_b32_e64 v2, 0, v2, s[44:45]
	v_cndmask_b32_e64 v3, 0, v3, s[44:45]
	v_cndmask_b32_e64 v4, 0, v4, s[44:45]
	v_cndmask_b32_e64 v5, 0, v5, s[44:45]
	global_store_dwordx4 v12, v[2:5], s[78:79] offset:0
	s_nop 0
	global_load_dword v58, v11, s[8:9]
	s_add_u32 s8, s8, 0x1000
	s_addc_u32 s9, s9, 0
	global_load_dword v59, v11, s[8:9]
	s_add_u32 s8, s8, 0x1000
	s_addc_u32 s9, s9, 0
	global_load_dword v60, v11, s[8:9]
	s_add_u32 s8, s8, 0x1000
	s_addc_u32 s9, s9, 0
	global_load_dword v61, v11, s[8:9]
	s_add_u32 s8, s8, 0x1000
	s_addc_u32 s9, s9, 0
	global_load_dword v62, v11, s[8:9]
	s_add_u32 s8, s8, 0x1000
	s_addc_u32 s9, s9, 0
	global_load_dword v63, v11, s[8:9]
	s_add_u32 s8, s8, 0x1000
	s_addc_u32 s9, s9, 0
	global_load_dword v64, v11, s[8:9]
	s_add_u32 s8, s8, 0x1000
	s_addc_u32 s9, s9, 0
	global_load_dword v65, v11, s[8:9]
	s_add_u32 s8, s8, 0x1000
	s_addc_u32 s9, s9, 0
	s_waitcnt vmcnt(25)
	v_cvt_pk_bf16_f32 v2, v34, v35
	v_cvt_pk_bf16_f32 v3, v36, v37
	v_cvt_pk_bf16_f32 v4, v38, v39
	v_cvt_pk_bf16_f32 v5, v40, v41
	v_cndmask_b32_e64 v2, 0, v2, s[44:45]
	v_cndmask_b32_e64 v3, 0, v3, s[44:45]
	v_cndmask_b32_e64 v4, 0, v4, s[44:45]
	v_cndmask_b32_e64 v5, 0, v5, s[44:45]
	global_store_dwordx4 v12, v[2:5], s[78:79] offset:16
	s_nop 0
	global_load_dword v66, v11, s[8:9]
	s_add_u32 s8, s8, 0x1000
	s_addc_u32 s9, s9, 0
	global_load_dword v67, v11, s[8:9]
	s_add_u32 s8, s8, 0x1000
	s_addc_u32 s9, s9, 0
	global_load_dword v68, v11, s[8:9]
	s_add_u32 s8, s8, 0x1000
	s_addc_u32 s9, s9, 0
	global_load_dword v69, v11, s[8:9]
	s_add_u32 s8, s8, 0x1000
	s_addc_u32 s9, s9, 0
	global_load_dword v70, v11, s[8:9]
	s_add_u32 s8, s8, 0x1000
	s_addc_u32 s9, s9, 0
	global_load_dword v71, v11, s[8:9]
	s_add_u32 s8, s8, 0x1000
	s_addc_u32 s9, s9, 0
	global_load_dword v72, v11, s[8:9]
	s_add_u32 s8, s8, 0x1000
	s_addc_u32 s9, s9, 0
	global_load_dword v73, v11, s[8:9]
	s_add_u32 s8, s8, 0x1000
	s_addc_u32 s9, s9, 0
	s_waitcnt vmcnt(26)
	v_cvt_pk_bf16_f32 v2, v42, v43
	v_cvt_pk_bf16_f32 v3, v44, v45
	v_cvt_pk_bf16_f32 v4, v46, v47
	v_cvt_pk_bf16_f32 v5, v48, v49
	v_cndmask_b32_e64 v2, 0, v2, s[44:45]
	v_cndmask_b32_e64 v3, 0, v3, s[44:45]
	v_cndmask_b32_e64 v4, 0, v4, s[44:45]
	v_cndmask_b32_e64 v5, 0, v5, s[44:45]
	global_store_dwordx4 v12, v[2:5], s[78:79] offset:32
	s_nop 0
	global_load_dword v74, v11, s[8:9]
	s_add_u32 s8, s8, 0x1000
	s_addc_u32 s9, s9, 0
	global_load_dword v75, v11, s[8:9]
	s_add_u32 s8, s8, 0x1000
	s_addc_u32 s9, s9, 0
	global_load_dword v76, v11, s[8:9]
	s_add_u32 s8, s8, 0x1000
	s_addc_u32 s9, s9, 0
	global_load_dword v77, v11, s[8:9]
	s_add_u32 s8, s8, 0x1000
	s_addc_u32 s9, s9, 0
	global_load_dword v78, v11, s[8:9]
	s_add_u32 s8, s8, 0x1000
	s_addc_u32 s9, s9, 0
	global_load_dword v79, v11, s[8:9]
	s_add_u32 s8, s8, 0x1000
	s_addc_u32 s9, s9, 0
	global_load_dword v80, v11, s[8:9]
	s_add_u32 s8, s8, 0x1000
	s_addc_u32 s9, s9, 0
	global_load_dword v81, v11, s[8:9]
	s_add_u32 s8, s8, 0x1000
	s_addc_u32 s9, s9, 0
	s_waitcnt vmcnt(27)
	v_cvt_pk_bf16_f32 v2, v50, v51
	v_cvt_pk_bf16_f32 v3, v52, v53
	v_cvt_pk_bf16_f32 v4, v54, v55
	v_cvt_pk_bf16_f32 v5, v56, v57
	v_cndmask_b32_e64 v2, 0, v2, s[44:45]
	v_cndmask_b32_e64 v3, 0, v3, s[44:45]
	v_cndmask_b32_e64 v4, 0, v4, s[44:45]
	v_cndmask_b32_e64 v5, 0, v5, s[44:45]
	global_store_dwordx4 v12, v[2:5], s[78:79] offset:48
	s_nop 0
	global_load_dword v82, v11, s[8:9]
	s_add_u32 s8, s8, 0x1000
	s_addc_u32 s9, s9, 0
	global_load_dword v83, v11, s[8:9]
	s_add_u32 s8, s8, 0x1000
	s_addc_u32 s9, s9, 0
	global_load_dword v84, v11, s[8:9]
	s_add_u32 s8, s8, 0x1000
	s_addc_u32 s9, s9, 0
	global_load_dword v85, v11, s[8:9]
	s_add_u32 s8, s8, 0x1000
	s_addc_u32 s9, s9, 0
	global_load_dword v86, v11, s[8:9]
	s_add_u32 s8, s8, 0x1000
	s_addc_u32 s9, s9, 0
	global_load_dword v87, v11, s[8:9]
	s_add_u32 s8, s8, 0x1000
	s_addc_u32 s9, s9, 0
	global_load_dword v88, v11, s[8:9]
	s_add_u32 s8, s8, 0x1000
	s_addc_u32 s9, s9, 0
	global_load_dword v89, v11, s[8:9]
	s_add_u32 s8, s8, 0x1000
	s_addc_u32 s9, s9, 0
	s_waitcnt vmcnt(27)
	v_cvt_pk_bf16_f32 v2, v58, v59
	v_cvt_pk_bf16_f32 v3, v60, v61
	v_cvt_pk_bf16_f32 v4, v62, v63
	v_cvt_pk_bf16_f32 v5, v64, v65
	v_cndmask_b32_e64 v2, 0, v2, s[44:45]
	v_cndmask_b32_e64 v3, 0, v3, s[44:45]
	v_cndmask_b32_e64 v4, 0, v4, s[44:45]
	v_cndmask_b32_e64 v5, 0, v5, s[44:45]
	global_store_dwordx4 v12, v[2:5], s[78:79] offset:64
	s_nop 0
	s_waitcnt vmcnt(19)
	v_cvt_pk_bf16_f32 v2, v66, v67
	v_cvt_pk_bf16_f32 v3, v68, v69
	v_cvt_pk_bf16_f32 v4, v70, v71
	v_cvt_pk_bf16_f32 v5, v72, v73
	v_cndmask_b32_e64 v2, 0, v2, s[44:45]
	v_cndmask_b32_e64 v3, 0, v3, s[44:45]
	v_cndmask_b32_e64 v4, 0, v4, s[44:45]
	v_cndmask_b32_e64 v5, 0, v5, s[44:45]
	global_store_dwordx4 v12, v[2:5], s[78:79] offset:80
	s_nop 0
	s_waitcnt vmcnt(11)
	v_cvt_pk_bf16_f32 v2, v74, v75
	v_cvt_pk_bf16_f32 v3, v76, v77
	v_cvt_pk_bf16_f32 v4, v78, v79
	v_cvt_pk_bf16_f32 v5, v80, v81
	v_cndmask_b32_e64 v2, 0, v2, s[44:45]
	v_cndmask_b32_e64 v3, 0, v3, s[44:45]
	v_cndmask_b32_e64 v4, 0, v4, s[44:45]
	v_cndmask_b32_e64 v5, 0, v5, s[44:45]
	global_store_dwordx4 v12, v[2:5], s[78:79] offset:96
	s_nop 0
	s_waitcnt vmcnt(3)
	v_cvt_pk_bf16_f32 v2, v82, v83
	v_cvt_pk_bf16_f32 v3, v84, v85
	v_cvt_pk_bf16_f32 v4, v86, v87
	v_cvt_pk_bf16_f32 v5, v88, v89
	v_cndmask_b32_e64 v2, 0, v2, s[44:45]
	v_cndmask_b32_e64 v3, 0, v3, s[44:45]
	v_cndmask_b32_e64 v4, 0, v4, s[44:45]
	v_cndmask_b32_e64 v5, 0, v5, s[44:45]
	global_store_dwordx4 v12, v[2:5], s[78:79] offset:112
	s_nop 0
	s_branch .Ltr_done
.Ltr_wuq:
	s_lshl_b32 s24, s22, 6
	v_add_u32_e32 v10, s24, v221
	v_mov_b32_e32 v11, v10
	v_cmp_gt_u32_e32 vcc, 0x180, v10
	s_mov_b64 s[44:45], vcc
	v_min_u32_e32 v11, 0x17f, v11
	v_lshlrev_b32_e32 v11, 2, v11
	s_mul_i32 s0, s28, 0x48000
	s_mul_i32 s1, s23, 0x18000
	s_add_u32 s8, s64, s0
	s_addc_u32 s9, s65, 0
	s_add_u32 s8, s8, s1
	s_addc_u32 s9, s9, 0
	v_mul_u32_u24_e32 v12, 0x180, v10
	s_lshl_b32 s0, s23, 7
	v_add_u32_e32 v12, s0, v12
	v_readlane_b32 s78, v253, 11
	v_readlane_b32 s79, v253, 12
	s_mul_i32 s0, s28, 0x30000
	s_add_u32 s78, s78, s0
	s_addc_u32 s79, s79, 0
	s_mul_i32 s0, s28, 0x300
	s_lshl_b32 s1, s23, 8
	s_add_u32 s20, s60, s0
	s_addc_u32 s21, s61, 0
	s_add_u32 s20, s20, s1
	s_addc_u32 s21, s21, 0
	global_load_dword v26, v11, s[8:9]
	s_add_u32 s8, s8, 0x600
	s_addc_u32 s9, s9, 0
	global_load_dword v27, v11, s[8:9]
	s_add_u32 s8, s8, 0x600
	s_addc_u32 s9, s9, 0
	global_load_dword v28, v11, s[8:9]
	s_add_u32 s8, s8, 0x600
	s_addc_u32 s9, s9, 0
	global_load_dword v29, v11, s[8:9]
	s_add_u32 s8, s8, 0x600
	s_addc_u32 s9, s9, 0
	global_load_dword v30, v11, s[8:9]
	s_add_u32 s8, s8, 0x600
	s_addc_u32 s9, s9, 0
	global_load_dword v31, v11, s[8:9]
	s_add_u32 s8, s8, 0x600
	s_addc_u32 s9, s9, 0
	global_load_dword v32, v11, s[8:9]
	s_add_u32 s8, s8, 0x600
	s_addc_u32 s9, s9, 0
	global_load_dword v33, v11, s[8:9]
	s_add_u32 s8, s8, 0x600
	s_addc_u32 s9, s9, 0
	global_load_dword v34, v11, s[8:9]
	s_add_u32 s8, s8, 0x600
	s_addc_u32 s9, s9, 0
	global_load_dword v35, v11, s[8:9]
	s_add_u32 s8, s8, 0x600
	s_addc_u32 s9, s9, 0
	global_load_dword v36, v11, s[8:9]
	s_add_u32 s8, s8, 0x600
	s_addc_u32 s9, s9, 0
	global_load_dword v37, v11, s[8:9]
	s_add_u32 s8, s8, 0x600
	s_addc_u32 s9, s9, 0
	global_load_dword v38, v11, s[8:9]
	s_add_u32 s8, s8, 0x600
	s_addc_u32 s9, s9, 0
	global_load_dword v39, v11, s[8:9]
	s_add_u32 s8, s8, 0x600
	s_addc_u32 s9, s9, 0
	global_load_dword v40, v11, s[8:9]
	s_add_u32 s8, s8, 0x600
	s_addc_u32 s9, s9, 0
	global_load_dword v41, v11, s[8:9]
	s_add_u32 s8, s8, 0x600
	s_addc_u32 s9, s9, 0
	global_load_dword v42, v11, s[8:9]
	s_add_u32 s8, s8, 0x600
	s_addc_u32 s9, s9, 0
	global_load_dword v43, v11, s[8:9]
	s_add_u32 s8, s8, 0x600
	s_addc_u32 s9, s9, 0
	global_load_dword v44, v11, s[8:9]
	s_add_u32 s8, s8, 0x600
	s_addc_u32 s9, s9, 0
	global_load_dword v45, v11, s[8:9]
	s_add_u32 s8, s8, 0x600
	s_addc_u32 s9, s9, 0
	global_load_dword v46, v11, s[8:9]
	s_add_u32 s8, s8, 0x600
	s_addc_u32 s9, s9, 0
	global_load_dword v47, v11, s[8:9]
	s_add_u32 s8, s8, 0x600
	s_addc_u32 s9, s9, 0
	global_load_dword v48, v11, s[8:9]
	s_add_u32 s8, s8, 0x600
	s_addc_u32 s9, s9, 0
	global_load_dword v49, v11, s[8:9]
	s_add_u32 s8, s8, 0x600
	s_addc_u32 s9, s9, 0
	global_load_dword v50, v11, s[8:9]
	s_add_u32 s8, s8, 0x600
	s_addc_u32 s9, s9, 0
	global_load_dword v51, v11, s[8:9]
	s_add_u32 s8, s8, 0x600
	s_addc_u32 s9, s9, 0
	global_load_dword v52, v11, s[8:9]
	s_add_u32 s8, s8, 0x600
	s_addc_u32 s9, s9, 0
	global_load_dword v53, v11, s[8:9]
	s_add_u32 s8, s8, 0x600
	s_addc_u32 s9, s9, 0
	global_load_dword v54, v11, s[8:9]
	s_add_u32 s8, s8, 0x600
	s_addc_u32 s9, s9, 0
	global_load_dword v55, v11, s[8:9]
	s_add_u32 s8, s8, 0x600
	s_addc_u32 s9, s9, 0
	global_load_dword v56, v11, s[8:9]
	s_add_u32 s8, s8, 0x600
	s_addc_u32 s9, s9, 0
	global_load_dword v57, v11, s[8:9]
	s_add_u32 s8, s8, 0x600
	s_addc_u32 s9, s9, 0
	s_load_dwordx8 s[88:95], s[20:21], 0x0
	s_waitcnt vmcnt(24)
	s_waitcnt lgkmcnt(0)
	v_mul_f32_e32 v26, s88, v26
	v_mul_f32_e32 v27, s89, v27
	v_mul_f32_e32 v28, s90, v28
	v_mul_f32_e32 v29, s91, v29
	v_mul_f32_e32 v30, s92, v30
	v_mul_f32_e32 v31, s93, v31
	v_mul_f32_e32 v32, s94, v32
	v_mul_f32_e32 v33, s95, v33
	v_cvt_pk_bf16_f32 v2, v26, v27
	v_cvt_pk_bf16_f32 v3, v28, v29
	v_cvt_pk_bf16_f32 v4, v30, v31
	v_cvt_pk_bf16_f32 v5, v32, v33
	v_cndmask_b32_e64 v2, 0, v2, s[44:45]
	v_cndmask_b32_e64 v3, 0, v3, s[44:45]
	v_cndmask_b32_e64 v4, 0, v4, s[44:45]
	v_cndmask_b32_e64 v5, 0, v5, s[44:45]
	global_store_dwordx4 v12, v[2:5], s[78:79] offset:0
	s_nop 0
	global_load_dword v58, v11, s[8:9]
	s_add_u32 s8, s8, 0x600
	s_addc_u32 s9, s9, 0
	global_load_dword v59, v11, s[8:9]
	s_add_u32 s8, s8, 0x600
	s_addc_u32 s9, s9, 0
	global_load_dword v60, v11, s[8:9]
	s_add_u32 s8, s8, 0x600
	s_addc_u32 s9, s9, 0
	global_load_dword v61, v11, s[8:9]
	s_add_u32 s8, s8, 0x600
	s_addc_u32 s9, s9, 0
	global_load_dword v62, v11, s[8:9]
	s_add_u32 s8, s8, 0x600
	s_addc_u32 s9, s9, 0
	global_load_dword v63, v11, s[8:9]
	s_add_u32 s8, s8, 0x600
	s_addc_u32 s9, s9, 0
	global_load_dword v64, v11, s[8:9]
	s_add_u32 s8, s8, 0x600
	s_addc_u32 s9, s9, 0
	global_load_dword v65, v11, s[8:9]
	s_add_u32 s8, s8, 0x600
	s_addc_u32 s9, s9, 0
	s_load_dwordx8 s[88:95], s[20:21], 0x20
	s_waitcnt vmcnt(25)
	s_waitcnt lgkmcnt(0)
	v_mul_f32_e32 v34, s88, v34
	v_mul_f32_e32 v35, s89, v35
	v_mul_f32_e32 v36, s90, v36
	v_mul_f32_e32 v37, s91, v37
	v_mul_f32_e32 v38, s92, v38
	v_mul_f32_e32 v39, s93, v39
	v_mul_f32_e32 v40, s94, v40
	v_mul_f32_e32 v41, s95, v41
	v_cvt_pk_bf16_f32 v2, v34, v35
	v_cvt_pk_bf16_f32 v3, v36, v37
	v_cvt_pk_bf16_f32 v4, v38, v39
	v_cvt_pk_bf16_f32 v5, v40, v41
	v_cndmask_b32_e64 v2, 0, v2, s[44:45]
	v_cndmask_b32_e64 v3, 0, v3, s[44:45]
	v_cndmask_b32_e64 v4, 0, v4, s[44:45]
	v_cndmask_b32_e64 v5, 0, v5, s[44:45]
	global_store_dwordx4 v12, v[2:5], s[78:79] offset:16
	s_nop 0
	global_load_dword v66, v11, s[8:9]
	s_add_u32 s8, s8, 0x600
	s_addc_u32 s9, s9, 0
	global_load_dword v67, v11, s[8:9]
	s_add_u32 s8, s8, 0x600
	s_addc_u32 s9, s9, 0
	global_load_dword v68, v11, s[8:9]
	s_add_u32 s8, s8, 0x600
	s_addc_u32 s9, s9, 0
	global_load_dword v69, v11, s[8:9]
	s_add_u32 s8, s8, 0x600
	s_addc_u32 s9, s9, 0
	global_load_dword v70, v11, s[8:9]
	s_add_u32 s8, s8, 0x600
	s_addc_u32 s9, s9, 0
	global_load_dword v71, v11, s[8:9]
	s_add_u32 s8, s8, 0x600
	s_addc_u32 s9, s9, 0
	global_load_dword v72, v11, s[8:9]
	s_add_u32 s8, s8, 0x600
	s_addc_u32 s9, s9, 0
	global_load_dword v73, v11, s[8:9]
	s_add_u32 s8, s8, 0x600
	s_addc_u32 s9, s9, 0
	s_load_dwordx8 s[88:95], s[20:21], 0x40
	s_waitcnt vmcnt(26)
	s_waitcnt lgkmcnt(0)
	v_mul_f32_e32 v42, s88, v42
	v_mul_f32_e32 v43, s89, v43
	v_mul_f32_e32 v44, s90, v44
	v_mul_f32_e32 v45, s91, v45
	v_mul_f32_e32 v46, s92, v46
	v_mul_f32_e32 v47, s93, v47
	v_mul_f32_e32 v48, s94, v48
	v_mul_f32_e32 v49, s95, v49
	v_cvt_pk_bf16_f32 v2, v42, v43
	v_cvt_pk_bf16_f32 v3, v44, v45
	v_cvt_pk_bf16_f32 v4, v46, v47
	v_cvt_pk_bf16_f32 v5, v48, v49
	v_cndmask_b32_e64 v2, 0, v2, s[44:45]
	v_cndmask_b32_e64 v3, 0, v3, s[44:45]
	v_cndmask_b32_e64 v4, 0, v4, s[44:45]
	v_cndmask_b32_e64 v5, 0, v5, s[44:45]
	global_store_dwordx4 v12, v[2:5], s[78:79] offset:32
	s_nop 0
	global_load_dword v74, v11, s[8:9]
	s_add_u32 s8, s8, 0x600
	s_addc_u32 s9, s9, 0
	global_load_dword v75, v11, s[8:9]
	s_add_u32 s8, s8, 0x600
	s_addc_u32 s9, s9, 0
	global_load_dword v76, v11, s[8:9]
	s_add_u32 s8, s8, 0x600
	s_addc_u32 s9, s9, 0
	global_load_dword v77, v11, s[8:9]
	s_add_u32 s8, s8, 0x600
	s_addc_u32 s9, s9, 0
	global_load_dword v78, v11, s[8:9]
	s_add_u32 s8, s8, 0x600
	s_addc_u32 s9, s9, 0
	global_load_dword v79, v11, s[8:9]
	s_add_u32 s8, s8, 0x600
	s_addc_u32 s9, s9, 0
	global_load_dword v80, v11, s[8:9]
	s_add_u32 s8, s8, 0x600
	s_addc_u32 s9, s9, 0
	global_load_dword v81, v11, s[8:9]
	s_add_u32 s8, s8, 0x600
	s_addc_u32 s9, s9, 0
	s_load_dwordx8 s[88:95], s[20:21], 0x60
	s_waitcnt vmcnt(27)
	s_waitcnt lgkmcnt(0)
	v_mul_f32_e32 v50, s88, v50
	v_mul_f32_e32 v51, s89, v51
	v_mul_f32_e32 v52, s90, v52
	v_mul_f32_e32 v53, s91, v53
	v_mul_f32_e32 v54, s92, v54
	v_mul_f32_e32 v55, s93, v55
	v_mul_f32_e32 v56, s94, v56
	v_mul_f32_e32 v57, s95, v57
	v_cvt_pk_bf16_f32 v2, v50, v51
	v_cvt_pk_bf16_f32 v3, v52, v53
	v_cvt_pk_bf16_f32 v4, v54, v55
	v_cvt_pk_bf16_f32 v5, v56, v57
	v_cndmask_b32_e64 v2, 0, v2, s[44:45]
	v_cndmask_b32_e64 v3, 0, v3, s[44:45]
	v_cndmask_b32_e64 v4, 0, v4, s[44:45]
	v_cndmask_b32_e64 v5, 0, v5, s[44:45]
	global_store_dwordx4 v12, v[2:5], s[78:79] offset:48
	s_nop 0
	global_load_dword v82, v11, s[8:9]
	s_add_u32 s8, s8, 0x600
	s_addc_u32 s9, s9, 0
	global_load_dword v83, v11, s[8:9]
	s_add_u32 s8, s8, 0x600
	s_addc_u32 s9, s9, 0
	global_load_dword v84, v11, s[8:9]
	s_add_u32 s8, s8, 0x600
	s_addc_u32 s9, s9, 0
	global_load_dword v85, v11, s[8:9]
	s_add_u32 s8, s8, 0x600
	s_addc_u32 s9, s9, 0
	global_load_dword v86, v11, s[8:9]
	s_add_u32 s8, s8, 0x600
	s_addc_u32 s9, s9, 0
	global_load_dword v87, v11, s[8:9]
	s_add_u32 s8, s8, 0x600
	s_addc_u32 s9, s9, 0
	global_load_dword v88, v11, s[8:9]
	s_add_u32 s8, s8, 0x600
	s_addc_u32 s9, s9, 0
	global_load_dword v89, v11, s[8:9]
	s_add_u32 s8, s8, 0x600
	s_addc_u32 s9, s9, 0
	s_load_dwordx8 s[88:95], s[20:21], 0x80
	s_waitcnt vmcnt(27)
	s_waitcnt lgkmcnt(0)
	v_mul_f32_e32 v58, s88, v58
	v_mul_f32_e32 v59, s89, v59
	v_mul_f32_e32 v60, s90, v60
	v_mul_f32_e32 v61, s91, v61
	v_mul_f32_e32 v62, s92, v62
	v_mul_f32_e32 v63, s93, v63
	v_mul_f32_e32 v64, s94, v64
	v_mul_f32_e32 v65, s95, v65
	v_cvt_pk_bf16_f32 v2, v58, v59
	v_cvt_pk_bf16_f32 v3, v60, v61
	v_cvt_pk_bf16_f32 v4, v62, v63
	v_cvt_pk_bf16_f32 v5, v64, v65
	v_cndmask_b32_e64 v2, 0, v2, s[44:45]
	v_cndmask_b32_e64 v3, 0, v3, s[44:45]
	v_cndmask_b32_e64 v4, 0, v4, s[44:45]
	v_cndmask_b32_e64 v5, 0, v5, s[44:45]
	global_store_dwordx4 v12, v[2:5], s[78:79] offset:64
	s_nop 0
	s_load_dwordx8 s[88:95], s[20:21], 0xa0
	s_waitcnt vmcnt(19)
	s_waitcnt lgkmcnt(0)
	v_mul_f32_e32 v66, s88, v66
	v_mul_f32_e32 v67, s89, v67
	v_mul_f32_e32 v68, s90, v68
	v_mul_f32_e32 v69, s91, v69
	v_mul_f32_e32 v70, s92, v70
	v_mul_f32_e32 v71, s93, v71
	v_mul_f32_e32 v72, s94, v72
	v_mul_f32_e32 v73, s95, v73
	v_cvt_pk_bf16_f32 v2, v66, v67
	v_cvt_pk_bf16_f32 v3, v68, v69
	v_cvt_pk_bf16_f32 v4, v70, v71
	v_cvt_pk_bf16_f32 v5, v72, v73
	v_cndmask_b32_e64 v2, 0, v2, s[44:45]
	v_cndmask_b32_e64 v3, 0, v3, s[44:45]
	v_cndmask_b32_e64 v4, 0, v4, s[44:45]
	v_cndmask_b32_e64 v5, 0, v5, s[44:45]
	global_store_dwordx4 v12, v[2:5], s[78:79] offset:80
	s_nop 0
	s_load_dwordx8 s[88:95], s[20:21], 0xc0
	s_waitcnt vmcnt(11)
	s_waitcnt lgkmcnt(0)
	v_mul_f32_e32 v74, s88, v74
	v_mul_f32_e32 v75, s89, v75
	v_mul_f32_e32 v76, s90, v76
	v_mul_f32_e32 v77, s91, v77
	v_mul_f32_e32 v78, s92, v78
	v_mul_f32_e32 v79, s93, v79
	v_mul_f32_e32 v80, s94, v80
	v_mul_f32_e32 v81, s95, v81
	v_cvt_pk_bf16_f32 v2, v74, v75
	v_cvt_pk_bf16_f32 v3, v76, v77
	v_cvt_pk_bf16_f32 v4, v78, v79
	v_cvt_pk_bf16_f32 v5, v80, v81
	v_cndmask_b32_e64 v2, 0, v2, s[44:45]
	v_cndmask_b32_e64 v3, 0, v3, s[44:45]
	v_cndmask_b32_e64 v4, 0, v4, s[44:45]
	v_cndmask_b32_e64 v5, 0, v5, s[44:45]
	global_store_dwordx4 v12, v[2:5], s[78:79] offset:96
	s_nop 0
	s_load_dwordx8 s[88:95], s[20:21], 0xe0
	s_waitcnt vmcnt(3)
	s_waitcnt lgkmcnt(0)
	v_mul_f32_e32 v82, s88, v82
	v_mul_f32_e32 v83, s89, v83
	v_mul_f32_e32 v84, s90, v84
	v_mul_f32_e32 v85, s91, v85
	v_mul_f32_e32 v86, s92, v86
	v_mul_f32_e32 v87, s93, v87
	v_mul_f32_e32 v88, s94, v88
	v_mul_f32_e32 v89, s95, v89
	v_cvt_pk_bf16_f32 v2, v82, v83
	v_cvt_pk_bf16_f32 v3, v84, v85
	v_cvt_pk_bf16_f32 v4, v86, v87
	v_cvt_pk_bf16_f32 v5, v88, v89
	v_cndmask_b32_e64 v2, 0, v2, s[44:45]
	v_cndmask_b32_e64 v3, 0, v3, s[44:45]
	v_cndmask_b32_e64 v4, 0, v4, s[44:45]
	v_cndmask_b32_e64 v5, 0, v5, s[44:45]
	global_store_dwordx4 v12, v[2:5], s[78:79] offset:112
	s_nop 0
	s_branch .Ltr_done
.Ltr_wukv:
	s_lshl_b32 s24, s22, 6
	v_add_u32_e32 v10, s24, v221
	v_mov_b32_e32 v11, v10
	v_cmp_gt_u32_e32 vcc, 0x200, v10
	s_mov_b64 s[44:45], vcc
	v_min_u32_e32 v11, 0x1ff, v11
	v_lshlrev_b32_e32 v11, 2, v11
	s_mul_i32 s0, s28, 0x40000
	s_mul_i32 s1, s23, 0x20000
	s_add_u32 s8, s66, s0
	s_addc_u32 s9, s67, 0
	s_add_u32 s8, s8, s1
	s_addc_u32 s9, s9, 0
	v_mul_u32_u24_e32 v12, 0x100, v10
	s_lshl_b32 s0, s23, 7
	v_add_u32_e32 v12, s0, v12
	v_readlane_b32 s78, v253, 13
	v_readlane_b32 s79, v253, 14
	s_mul_i32 s0, s28, 0x20000
	s_add_u32 s78, s78, s0
	s_addc_u32 s79, s79, 0
	s_mul_i32 s0, s28, 0x200
	s_lshl_b32 s1, s23, 8
	s_add_u32 s20, s62, s0
	s_addc_u32 s21, s63, 0
	s_add_u32 s20, s20, s1
	s_addc_u32 s21, s21, 0
	global_load_dword v26, v11, s[8:9]
	s_add_u32 s8, s8, 0x800
	s_addc_u32 s9, s9, 0
	global_load_dword v27, v11, s[8:9]
	s_add_u32 s8, s8, 0x800
	s_addc_u32 s9, s9, 0
	global_load_dword v28, v11, s[8:9]
	s_add_u32 s8, s8, 0x800
	s_addc_u32 s9, s9, 0
	global_load_dword v29, v11, s[8:9]
	s_add_u32 s8, s8, 0x800
	s_addc_u32 s9, s9, 0
	global_load_dword v30, v11, s[8:9]
	s_add_u32 s8, s8, 0x800
	s_addc_u32 s9, s9, 0
	global_load_dword v31, v11, s[8:9]
	s_add_u32 s8, s8, 0x800
	s_addc_u32 s9, s9, 0
	global_load_dword v32, v11, s[8:9]
	s_add_u32 s8, s8, 0x800
	s_addc_u32 s9, s9, 0
	global_load_dword v33, v11, s[8:9]
	s_add_u32 s8, s8, 0x800
	s_addc_u32 s9, s9, 0
	global_load_dword v34, v11, s[8:9]
	s_add_u32 s8, s8, 0x800
	s_addc_u32 s9, s9, 0
	global_load_dword v35, v11, s[8:9]
	s_add_u32 s8, s8, 0x800
	s_addc_u32 s9, s9, 0
	global_load_dword v36, v11, s[8:9]
	s_add_u32 s8, s8, 0x800
	s_addc_u32 s9, s9, 0
	global_load_dword v37, v11, s[8:9]
	s_add_u32 s8, s8, 0x800
	s_addc_u32 s9, s9, 0
	global_load_dword v38, v11, s[8:9]
	s_add_u32 s8, s8, 0x800
	s_addc_u32 s9, s9, 0
	global_load_dword v39, v11, s[8:9]
	s_add_u32 s8, s8, 0x800
	s_addc_u32 s9, s9, 0
	global_load_dword v40, v11, s[8:9]
	s_add_u32 s8, s8, 0x800
	s_addc_u32 s9, s9, 0
	global_load_dword v41, v11, s[8:9]
	s_add_u32 s8, s8, 0x800
	s_addc_u32 s9, s9, 0
	global_load_dword v42, v11, s[8:9]
	s_add_u32 s8, s8, 0x800
	s_addc_u32 s9, s9, 0
	global_load_dword v43, v11, s[8:9]
	s_add_u32 s8, s8, 0x800
	s_addc_u32 s9, s9, 0
	global_load_dword v44, v11, s[8:9]
	s_add_u32 s8, s8, 0x800
	s_addc_u32 s9, s9, 0
	global_load_dword v45, v11, s[8:9]
	s_add_u32 s8, s8, 0x800
	s_addc_u32 s9, s9, 0
	global_load_dword v46, v11, s[8:9]
	s_add_u32 s8, s8, 0x800
	s_addc_u32 s9, s9, 0
	global_load_dword v47, v11, s[8:9]
	s_add_u32 s8, s8, 0x800
	s_addc_u32 s9, s9, 0
	global_load_dword v48, v11, s[8:9]
	s_add_u32 s8, s8, 0x800
	s_addc_u32 s9, s9, 0
	global_load_dword v49, v11, s[8:9]
	s_add_u32 s8, s8, 0x800
	s_addc_u32 s9, s9, 0
	global_load_dword v50, v11, s[8:9]
	s_add_u32 s8, s8, 0x800
	s_addc_u32 s9, s9, 0
	global_load_dword v51, v11, s[8:9]
	s_add_u32 s8, s8, 0x800
	s_addc_u32 s9, s9, 0
	global_load_dword v52, v11, s[8:9]
	s_add_u32 s8, s8, 0x800
	s_addc_u32 s9, s9, 0
	global_load_dword v53, v11, s[8:9]
	s_add_u32 s8, s8, 0x800
	s_addc_u32 s9, s9, 0
	global_load_dword v54, v11, s[8:9]
	s_add_u32 s8, s8, 0x800
	s_addc_u32 s9, s9, 0
	global_load_dword v55, v11, s[8:9]
	s_add_u32 s8, s8, 0x800
	s_addc_u32 s9, s9, 0
	global_load_dword v56, v11, s[8:9]
	s_add_u32 s8, s8, 0x800
	s_addc_u32 s9, s9, 0
	global_load_dword v57, v11, s[8:9]
	s_add_u32 s8, s8, 0x800
	s_addc_u32 s9, s9, 0
	s_load_dwordx8 s[88:95], s[20:21], 0x0
	s_waitcnt vmcnt(24)
	s_waitcnt lgkmcnt(0)
	v_mul_f32_e32 v26, s88, v26
	v_mul_f32_e32 v27, s89, v27
	v_mul_f32_e32 v28, s90, v28
	v_mul_f32_e32 v29, s91, v29
	v_mul_f32_e32 v30, s92, v30
	v_mul_f32_e32 v31, s93, v31
	v_mul_f32_e32 v32, s94, v32
	v_mul_f32_e32 v33, s95, v33
	v_cvt_pk_bf16_f32 v2, v26, v27
	v_cvt_pk_bf16_f32 v3, v28, v29
	v_cvt_pk_bf16_f32 v4, v30, v31
	v_cvt_pk_bf16_f32 v5, v32, v33
	v_cndmask_b32_e64 v2, 0, v2, s[44:45]
	v_cndmask_b32_e64 v3, 0, v3, s[44:45]
	v_cndmask_b32_e64 v4, 0, v4, s[44:45]
	v_cndmask_b32_e64 v5, 0, v5, s[44:45]
	global_store_dwordx4 v12, v[2:5], s[78:79] offset:0
	s_nop 0
	global_load_dword v58, v11, s[8:9]
	s_add_u32 s8, s8, 0x800
	s_addc_u32 s9, s9, 0
	global_load_dword v59, v11, s[8:9]
	s_add_u32 s8, s8, 0x800
	s_addc_u32 s9, s9, 0
	global_load_dword v60, v11, s[8:9]
	s_add_u32 s8, s8, 0x800
	s_addc_u32 s9, s9, 0
	global_load_dword v61, v11, s[8:9]
	s_add_u32 s8, s8, 0x800
	s_addc_u32 s9, s9, 0
	global_load_dword v62, v11, s[8:9]
	s_add_u32 s8, s8, 0x800
	s_addc_u32 s9, s9, 0
	global_load_dword v63, v11, s[8:9]
	s_add_u32 s8, s8, 0x800
	s_addc_u32 s9, s9, 0
	global_load_dword v64, v11, s[8:9]
	s_add_u32 s8, s8, 0x800
	s_addc_u32 s9, s9, 0
	global_load_dword v65, v11, s[8:9]
	s_add_u32 s8, s8, 0x800
	s_addc_u32 s9, s9, 0
	s_load_dwordx8 s[88:95], s[20:21], 0x20
	s_waitcnt vmcnt(25)
	s_waitcnt lgkmcnt(0)
	v_mul_f32_e32 v34, s88, v34
	v_mul_f32_e32 v35, s89, v35
	v_mul_f32_e32 v36, s90, v36
	v_mul_f32_e32 v37, s91, v37
	v_mul_f32_e32 v38, s92, v38
	v_mul_f32_e32 v39, s93, v39
	v_mul_f32_e32 v40, s94, v40
	v_mul_f32_e32 v41, s95, v41
	v_cvt_pk_bf16_f32 v2, v34, v35
	v_cvt_pk_bf16_f32 v3, v36, v37
	v_cvt_pk_bf16_f32 v4, v38, v39
	v_cvt_pk_bf16_f32 v5, v40, v41
	v_cndmask_b32_e64 v2, 0, v2, s[44:45]
	v_cndmask_b32_e64 v3, 0, v3, s[44:45]
	v_cndmask_b32_e64 v4, 0, v4, s[44:45]
	v_cndmask_b32_e64 v5, 0, v5, s[44:45]
	global_store_dwordx4 v12, v[2:5], s[78:79] offset:16
	s_nop 0
	global_load_dword v66, v11, s[8:9]
	s_add_u32 s8, s8, 0x800
	s_addc_u32 s9, s9, 0
	global_load_dword v67, v11, s[8:9]
	s_add_u32 s8, s8, 0x800
	s_addc_u32 s9, s9, 0
	global_load_dword v68, v11, s[8:9]
	s_add_u32 s8, s8, 0x800
	s_addc_u32 s9, s9, 0
	global_load_dword v69, v11, s[8:9]
	s_add_u32 s8, s8, 0x800
	s_addc_u32 s9, s9, 0
	global_load_dword v70, v11, s[8:9]
	s_add_u32 s8, s8, 0x800
	s_addc_u32 s9, s9, 0
	global_load_dword v71, v11, s[8:9]
	s_add_u32 s8, s8, 0x800
	s_addc_u32 s9, s9, 0
	global_load_dword v72, v11, s[8:9]
	s_add_u32 s8, s8, 0x800
	s_addc_u32 s9, s9, 0
	global_load_dword v73, v11, s[8:9]
	s_add_u32 s8, s8, 0x800
	s_addc_u32 s9, s9, 0
	s_load_dwordx8 s[88:95], s[20:21], 0x40
	s_waitcnt vmcnt(26)
	s_waitcnt lgkmcnt(0)
	v_mul_f32_e32 v42, s88, v42
	v_mul_f32_e32 v43, s89, v43
	v_mul_f32_e32 v44, s90, v44
	v_mul_f32_e32 v45, s91, v45
	v_mul_f32_e32 v46, s92, v46
	v_mul_f32_e32 v47, s93, v47
	v_mul_f32_e32 v48, s94, v48
	v_mul_f32_e32 v49, s95, v49
	v_cvt_pk_bf16_f32 v2, v42, v43
	v_cvt_pk_bf16_f32 v3, v44, v45
	v_cvt_pk_bf16_f32 v4, v46, v47
	v_cvt_pk_bf16_f32 v5, v48, v49
	v_cndmask_b32_e64 v2, 0, v2, s[44:45]
	v_cndmask_b32_e64 v3, 0, v3, s[44:45]
	v_cndmask_b32_e64 v4, 0, v4, s[44:45]
	v_cndmask_b32_e64 v5, 0, v5, s[44:45]
	global_store_dwordx4 v12, v[2:5], s[78:79] offset:32
	s_nop 0
	global_load_dword v74, v11, s[8:9]
	s_add_u32 s8, s8, 0x800
	s_addc_u32 s9, s9, 0
	global_load_dword v75, v11, s[8:9]
	s_add_u32 s8, s8, 0x800
	s_addc_u32 s9, s9, 0
	global_load_dword v76, v11, s[8:9]
	s_add_u32 s8, s8, 0x800
	s_addc_u32 s9, s9, 0
	global_load_dword v77, v11, s[8:9]
	s_add_u32 s8, s8, 0x800
	s_addc_u32 s9, s9, 0
	global_load_dword v78, v11, s[8:9]
	s_add_u32 s8, s8, 0x800
	s_addc_u32 s9, s9, 0
	global_load_dword v79, v11, s[8:9]
	s_add_u32 s8, s8, 0x800
	s_addc_u32 s9, s9, 0
	global_load_dword v80, v11, s[8:9]
	s_add_u32 s8, s8, 0x800
	s_addc_u32 s9, s9, 0
	global_load_dword v81, v11, s[8:9]
	s_add_u32 s8, s8, 0x800
	s_addc_u32 s9, s9, 0
	s_load_dwordx8 s[88:95], s[20:21], 0x60
	s_waitcnt vmcnt(27)
	s_waitcnt lgkmcnt(0)
	v_mul_f32_e32 v50, s88, v50
	v_mul_f32_e32 v51, s89, v51
	v_mul_f32_e32 v52, s90, v52
	v_mul_f32_e32 v53, s91, v53
	v_mul_f32_e32 v54, s92, v54
	v_mul_f32_e32 v55, s93, v55
	v_mul_f32_e32 v56, s94, v56
	v_mul_f32_e32 v57, s95, v57
	v_cvt_pk_bf16_f32 v2, v50, v51
	v_cvt_pk_bf16_f32 v3, v52, v53
	v_cvt_pk_bf16_f32 v4, v54, v55
	v_cvt_pk_bf16_f32 v5, v56, v57
	v_cndmask_b32_e64 v2, 0, v2, s[44:45]
	v_cndmask_b32_e64 v3, 0, v3, s[44:45]
	v_cndmask_b32_e64 v4, 0, v4, s[44:45]
	v_cndmask_b32_e64 v5, 0, v5, s[44:45]
	global_store_dwordx4 v12, v[2:5], s[78:79] offset:48
	s_nop 0
	global_load_dword v82, v11, s[8:9]
	s_add_u32 s8, s8, 0x800
	s_addc_u32 s9, s9, 0
	global_load_dword v83, v11, s[8:9]
	s_add_u32 s8, s8, 0x800
	s_addc_u32 s9, s9, 0
	global_load_dword v84, v11, s[8:9]
	s_add_u32 s8, s8, 0x800
	s_addc_u32 s9, s9, 0
	global_load_dword v85, v11, s[8:9]
	s_add_u32 s8, s8, 0x800
	s_addc_u32 s9, s9, 0
	global_load_dword v86, v11, s[8:9]
	s_add_u32 s8, s8, 0x800
	s_addc_u32 s9, s9, 0
	global_load_dword v87, v11, s[8:9]
	s_add_u32 s8, s8, 0x800
	s_addc_u32 s9, s9, 0
	global_load_dword v88, v11, s[8:9]
	s_add_u32 s8, s8, 0x800
	s_addc_u32 s9, s9, 0
	global_load_dword v89, v11, s[8:9]
	s_add_u32 s8, s8, 0x800
	s_addc_u32 s9, s9, 0
	s_load_dwordx8 s[88:95], s[20:21], 0x80
	s_waitcnt vmcnt(27)
	s_waitcnt lgkmcnt(0)
	v_mul_f32_e32 v58, s88, v58
	v_mul_f32_e32 v59, s89, v59
	v_mul_f32_e32 v60, s90, v60
	v_mul_f32_e32 v61, s91, v61
	v_mul_f32_e32 v62, s92, v62
	v_mul_f32_e32 v63, s93, v63
	v_mul_f32_e32 v64, s94, v64
	v_mul_f32_e32 v65, s95, v65
	v_cvt_pk_bf16_f32 v2, v58, v59
	v_cvt_pk_bf16_f32 v3, v60, v61
	v_cvt_pk_bf16_f32 v4, v62, v63
	v_cvt_pk_bf16_f32 v5, v64, v65
	v_cndmask_b32_e64 v2, 0, v2, s[44:45]
	v_cndmask_b32_e64 v3, 0, v3, s[44:45]
	v_cndmask_b32_e64 v4, 0, v4, s[44:45]
	v_cndmask_b32_e64 v5, 0, v5, s[44:45]
	global_store_dwordx4 v12, v[2:5], s[78:79] offset:64
	s_nop 0
	s_load_dwordx8 s[88:95], s[20:21], 0xa0
	s_waitcnt vmcnt(19)
	s_waitcnt lgkmcnt(0)
	v_mul_f32_e32 v66, s88, v66
	v_mul_f32_e32 v67, s89, v67
	v_mul_f32_e32 v68, s90, v68
	v_mul_f32_e32 v69, s91, v69
	v_mul_f32_e32 v70, s92, v70
	v_mul_f32_e32 v71, s93, v71
	v_mul_f32_e32 v72, s94, v72
	v_mul_f32_e32 v73, s95, v73
	v_cvt_pk_bf16_f32 v2, v66, v67
	v_cvt_pk_bf16_f32 v3, v68, v69
	v_cvt_pk_bf16_f32 v4, v70, v71
	v_cvt_pk_bf16_f32 v5, v72, v73
	v_cndmask_b32_e64 v2, 0, v2, s[44:45]
	v_cndmask_b32_e64 v3, 0, v3, s[44:45]
	v_cndmask_b32_e64 v4, 0, v4, s[44:45]
	v_cndmask_b32_e64 v5, 0, v5, s[44:45]
	global_store_dwordx4 v12, v[2:5], s[78:79] offset:80
	s_nop 0
	s_load_dwordx8 s[88:95], s[20:21], 0xc0
	s_waitcnt vmcnt(11)
	s_waitcnt lgkmcnt(0)
	v_mul_f32_e32 v74, s88, v74
	v_mul_f32_e32 v75, s89, v75
	v_mul_f32_e32 v76, s90, v76
	v_mul_f32_e32 v77, s91, v77
	v_mul_f32_e32 v78, s92, v78
	v_mul_f32_e32 v79, s93, v79
	v_mul_f32_e32 v80, s94, v80
	v_mul_f32_e32 v81, s95, v81
	v_cvt_pk_bf16_f32 v2, v74, v75
	v_cvt_pk_bf16_f32 v3, v76, v77
	v_cvt_pk_bf16_f32 v4, v78, v79
	v_cvt_pk_bf16_f32 v5, v80, v81
	v_cndmask_b32_e64 v2, 0, v2, s[44:45]
	v_cndmask_b32_e64 v3, 0, v3, s[44:45]
	v_cndmask_b32_e64 v4, 0, v4, s[44:45]
	v_cndmask_b32_e64 v5, 0, v5, s[44:45]
	global_store_dwordx4 v12, v[2:5], s[78:79] offset:96
	s_nop 0
	s_load_dwordx8 s[88:95], s[20:21], 0xe0
	s_waitcnt vmcnt(3)
	s_waitcnt lgkmcnt(0)
	v_mul_f32_e32 v82, s88, v82
	v_mul_f32_e32 v83, s89, v83
	v_mul_f32_e32 v84, s90, v84
	v_mul_f32_e32 v85, s91, v85
	v_mul_f32_e32 v86, s92, v86
	v_mul_f32_e32 v87, s93, v87
	v_mul_f32_e32 v88, s94, v88
	v_mul_f32_e32 v89, s95, v89
	v_cvt_pk_bf16_f32 v2, v82, v83
	v_cvt_pk_bf16_f32 v3, v84, v85
	v_cvt_pk_bf16_f32 v4, v86, v87
	v_cvt_pk_bf16_f32 v5, v88, v89
	v_cndmask_b32_e64 v2, 0, v2, s[44:45]
	v_cndmask_b32_e64 v3, 0, v3, s[44:45]
	v_cndmask_b32_e64 v4, 0, v4, s[44:45]
	v_cndmask_b32_e64 v5, 0, v5, s[44:45]
	global_store_dwordx4 v12, v[2:5], s[78:79] offset:112
	s_nop 0
	s_branch .Ltr_done

.Lxb_release:
	s_mov_b64 exec, 0xffff
	v_mbcnt_lo_u32_b32 v3, -1, 0
	v_mov_b32_e32 v2, 1
	v_lshlrev_b32_e32 v3, 8, v3
	global_atomic_add v3, v2, s[38:39]
	s_mov_b64 exec, 1
	s_branch .Lxb_acq
